# scan loaders: drain wait before the next-chunk loads removed (it only covered the y store)
# speedup vs baseline: 1.0077x; 1.0077x over previous
.LBB0_824:
	v_lshl_add_u64 v[24:25], v[92:93], 0, s[34:35]
	v_add_co_u32_e32 v0, vcc, 0x16bfe000, v24
	s_nop 1
	v_addc_co_u32_e32 v1, vcc, 0, v25, vcc
	v_add_co_u32_e32 v4, vcc, 0x16bff000, v24
	s_nop 1
	v_addc_co_u32_e32 v5, vcc, 0, v25, vcc
	v_add_co_u32_e32 v8, vcc, 0x16c00000, v24
	global_load_dwordx4 v[0:3], v[0:1], off
	s_nop 0
	global_load_dwordx4 v[4:7], v[4:5], off
	v_addc_co_u32_e32 v9, vcc, 0, v25, vcc
	v_add_co_u32_e32 v12, vcc, 0x16c01000, v24
	s_nop 1
	v_addc_co_u32_e32 v13, vcc, 0, v25, vcc
	v_add_co_u32_e32 v16, vcc, 0x16c02000, v24
	global_load_dwordx4 v[8:11], v[8:9], off
	s_nop 0
	global_load_dwordx4 v[12:15], v[12:13], off
	v_addc_co_u32_e32 v17, vcc, 0, v25, vcc
	v_add_co_u32_e32 v20, vcc, 0x16c03000, v24
	s_nop 1
	v_addc_co_u32_e32 v21, vcc, 0, v25, vcc
	v_add_co_u32_e32 v24, vcc, 0x16c04000, v24
	global_load_dwordx4 v[16:19], v[16:17], off
	s_nop 0
	global_load_dwordx4 v[20:23], v[20:21], off
	v_addc_co_u32_e32 v25, vcc, 0, v25, vcc
	global_load_dwordx4 v[24:27], v[24:25], off
	s_cmp_eq_u32 s34, 0
	s_cbranch_scc1 .LBB0_786
